# v15 + P3 conv rows kept in registers (16 v_mov) instead of LDS write/read round trip
# speedup vs baseline: 1.0156x; 1.0070x over previous
.Lev_skip_a:
	s_add_i32 s34, s49, 3
	v_sub_u32_e64 v32, 60, s44 clamp
	s_and_b64 s[20:21], exec, s[38:39]
	v_readfirstlane_b32 s20, v32
	s_cselect_b32 s66, s34, s20
	s_lshl_b32 s34, s66, 13
	s_lshl_b32 s67, s66, 14
	s_add_u32 s20, s43, s67
	s_addc_u32 s21, s63, 0
	v_lshl_add_u64 v[36:37], s[20:21], 0, v[120:121]
	global_load_dwordx4 v[32:35], v120, s[20:21]
	v_add_co_u32_e64 v36, s[20:21], s60, v36
	v_lshl_add_u64 v[48:49], v[146:147], 0, s[34:35]
	s_nop 0
	v_addc_co_u32_e64 v37, s[20:21], 0, v37, s[20:21]
	s_add_u32 s20, s64, s67
	s_addc_u32 s21, s65, 0
	v_lshl_add_u64 v[44:45], s[20:21], 0, v[120:121]
	global_load_dwordx4 v[36:39], v[36:37], off
	s_lshl_b32 s34, s66, 10
	global_load_dwordx4 v[40:43], v120, s[20:21]
	v_add_co_u32_e64 v44, s[20:21], s60, v44
	v_lshl_add_u64 v[52:53], v[148:149], 0, s[34:35]
	s_nop 0
	v_addc_co_u32_e64 v45, s[20:21], 0, v45, s[20:21]
	s_lshl_b32 s20, s49, 1
	s_add_i32 s34, s20, 4
	s_waitcnt vmcnt(15)
	v_mov_b32_e32 v214, v64
	v_mov_b32_e32 v215, v65
	v_mov_b32_e32 v216, v66
	v_mov_b32_e32 v217, v67
	v_lshl_add_u64 v[64:65], v[144:145], 0, s[34:35]
	s_add_i32 s34, 0, 0x1e400
	v_mov_b32_e32 v198, v56
	v_mov_b32_e32 v199, v57
	v_mov_b32_e32 v200, v58
	v_mov_b32_e32 v201, v59
	v_mov_b32_e32 v202, v60
	v_mov_b32_e32 v203, v61
	v_mov_b32_e32 v204, v62
	v_mov_b32_e32 v205, v63
	s_waitcnt vmcnt(14)
	v_mov_b32_e32 v242, v68
	v_mov_b32_e32 v243, v69
	v_mov_b32_e32 v244, v70
	v_mov_b32_e32 v245, v71
	v_add_u32_e32 v116, s34, v143
	ds_read_b128 v[190:193], v116
	v_and_b32_e32 v66, 0xfff, v64
	v_cmp_ne_u32_e64 s[20:21], 0, v66
	v_add_u32_e32 v185, 0, v143
	v_add_u32_e32 v116, 0x1e600, v185
	s_waitcnt lgkmcnt(0)
	v_pk_mul_f32 v[192:193], v[98:99], v[192:193]
	v_pk_mul_f32 v[190:191], v[96:97], v[190:191]
	v_pk_mul_f32 v[98:99], v[102:103], v[192:193]
	v_pk_mul_f32 v[96:97], v[100:101], v[190:191]
	v_cndmask_b32_e64 v56, 0, 1, s[20:21]
	v_cvt_pk_bf16_f32 v100, v96, v97
	v_cvt_pk_bf16_f32 v101, v98, v99
	v_sub_co_u32_e64 v56, s[20:21], v64, v56
	ds_read_b128 v[116:119], v116
	ds_write_b64 v182, v[100:101]
	v_pk_mul_f32 v[100:101], v[104:105], v[190:191]
	v_pk_mul_f32 v[102:103], v[106:107], v[192:193]
	v_subbrev_co_u32_e64 v57, s[20:21], 0, v65, s[20:21]
	v_cvt_pk_bf16_f32 v104, v100, v101
	v_cvt_pk_bf16_f32 v105, v102, v103
	v_cmp_ne_u32_e64 s[20:21], s62, v66
	ds_write_b64 v182, v[104:105] offset:4352
	v_pk_mul_f32 v[104:105], v[108:109], v[190:191]
	v_pk_mul_f32 v[106:107], v[110:111], v[192:193]
	v_cndmask_b32_e64 v66, 0, 1, s[20:21]
	v_mov_b32_e32 v67, s35
	v_cvt_pk_bf16_f32 v108, v104, v105
	v_cvt_pk_bf16_f32 v109, v106, v107
	v_lshlrev_b64 v[68:69], 11, v[64:65]
	v_lshl_add_u64 v[64:65], v[64:65], 0, v[66:67]
	ds_write_b64 v182, v[108:109] offset:8704
	v_pk_mul_f32 v[108:109], v[112:113], v[190:191]
	v_pk_mul_f32 v[110:111], v[114:115], v[192:193]
	v_lshlrev_b64 v[56:57], 11, v[56:57]
	v_lshlrev_b64 v[64:65], 11, v[64:65]
	v_cvt_pk_bf16_f32 v112, v108, v109
	v_cvt_pk_bf16_f32 v113, v110, v111
	v_lshl_add_u64 v[56:57], v[134:135], 0, v[56:57]
	v_lshl_add_u64 v[60:61], v[134:135], 0, v[68:69]
	v_lshl_add_u64 v[64:65], v[134:135], 0, v[64:65]
	v_lshl_add_u64 v[68:69], v[136:137], 0, v[68:69]
	ds_write_b64 v182, v[112:113] offset:13056
	global_load_dwordx4 v[44:47], v[44:45], off
	global_load_dwordx4 v[48:51], v[48:49], off
	global_load_dwordx4 v[52:55], v[52:53], off
	global_load_dwordx4 v[56:59], v[56:57], off
	s_lshl_b32 s48, s48, 6
	global_load_dwordx4 v[60:63], v[60:61], off
	s_nop 0
	global_load_dwordx4 v[64:67], v[64:65], off
	s_nop 0
	global_load_dwordx4 v[68:71], v[68:69], off
	s_waitcnt lgkmcnt(0)
	s_barrier
	ds_read_b128 v[218:221], v170 offset:61440
	ds_read_b128 v[222:225], v171 offset:44032
	ds_read_b128 v[226:229], v172 offset:44032
	ds_read_b64_tr_b16 v[230:231], v178 offset:17408
	ds_read_b64_tr_b16 v[232:233], v178 offset:18496
	ds_read_b64_tr_b16 v[234:235], v161 offset:34816
	ds_read_b64_tr_b16 v[236:237], v161 offset:35392
	ds_read_b64_tr_b16 v[238:239], v161 offset:34848
	ds_read_b64_tr_b16 v[240:241], v161 offset:35424
	v_and_b32_e32 v250, 0xfff, v184
	v_cmp_ne_u32_e64 s[20:21], 0, v250
	v_add_u32_e32 v184, 4, v184
	v_cndmask_b32_e64 v198, 0, v198, s[20:21]
	v_cndmask_b32_e64 v199, 0, v199, s[20:21]
	v_cndmask_b32_e64 v200, 0, v200, s[20:21]
	v_cndmask_b32_e64 v201, 0, v201, s[20:21]
	v_cmp_ne_u32_e64 s[20:21], s62, v250
	v_lshlrev_b32_e32 v246, 16, v202
	v_and_b32_e32 v247, 0xffff0000, v202
	v_cndmask_b32_e64 v214, 0, v214, s[20:21]
	v_cndmask_b32_e64 v215, 0, v215, s[20:21]
	v_cndmask_b32_e64 v216, 0, v216, s[20:21]
	v_cndmask_b32_e64 v217, 0, v217, s[20:21]
	v_pk_mul_f32 v[246:247], v[8:9], v[246:247]
	v_lshlrev_b32_e32 v248, 16, v198
	v_and_b32_e32 v249, 0xffff0000, v198
	v_pk_fma_f32 v[246:247], v[0:1], v[248:249], v[246:247]
	v_lshlrev_b32_e32 v248, 16, v214
	v_and_b32_e32 v249, 0xffff0000, v214
	v_pk_fma_f32 v[246:247], v[16:17], v[248:249], v[246:247]
	v_pk_add_f32 v[246:247], v[24:25], v[246:247]
	v_lshlrev_b32_e32 v248, 16, v242
	v_and_b32_e32 v249, 0xffff0000, v242
	v_pk_mul_f32 v[246:247], v[246:247], v[248:249]
	v_cvt_pk_bf16_f32 v198, v246, v247
	v_lshlrev_b32_e32 v246, 16, v203
	v_and_b32_e32 v247, 0xffff0000, v203
	v_pk_mul_f32 v[246:247], v[10:11], v[246:247]
	v_lshlrev_b32_e32 v248, 16, v199
	v_and_b32_e32 v249, 0xffff0000, v199
	v_pk_fma_f32 v[246:247], v[2:3], v[248:249], v[246:247]
	v_lshlrev_b32_e32 v248, 16, v215
	v_and_b32_e32 v249, 0xffff0000, v215
	v_pk_fma_f32 v[246:247], v[18:19], v[248:249], v[246:247]
	v_pk_add_f32 v[246:247], v[26:27], v[246:247]
	v_lshlrev_b32_e32 v248, 16, v243
	v_and_b32_e32 v249, 0xffff0000, v243
	v_pk_mul_f32 v[246:247], v[246:247], v[248:249]
	v_cvt_pk_bf16_f32 v199, v246, v247
	v_lshlrev_b32_e32 v246, 16, v204
	v_and_b32_e32 v247, 0xffff0000, v204
	v_pk_mul_f32 v[246:247], v[12:13], v[246:247]
	v_lshlrev_b32_e32 v248, 16, v200
	v_and_b32_e32 v249, 0xffff0000, v200
	v_pk_fma_f32 v[246:247], v[4:5], v[248:249], v[246:247]
	v_lshlrev_b32_e32 v248, 16, v216
	v_and_b32_e32 v249, 0xffff0000, v216
	v_pk_fma_f32 v[246:247], v[20:21], v[248:249], v[246:247]
	v_pk_add_f32 v[246:247], v[28:29], v[246:247]
	v_lshlrev_b32_e32 v248, 16, v244
	v_and_b32_e32 v249, 0xffff0000, v244
	v_pk_mul_f32 v[246:247], v[246:247], v[248:249]
	v_cvt_pk_bf16_f32 v200, v246, v247
	v_lshlrev_b32_e32 v246, 16, v205
	v_and_b32_e32 v247, 0xffff0000, v205
	v_pk_mul_f32 v[246:247], v[14:15], v[246:247]
	v_lshlrev_b32_e32 v248, 16, v201
	v_and_b32_e32 v249, 0xffff0000, v201
	v_pk_fma_f32 v[246:247], v[6:7], v[248:249], v[246:247]
	v_lshlrev_b32_e32 v248, 16, v217
	v_and_b32_e32 v249, 0xffff0000, v217
	v_pk_fma_f32 v[246:247], v[22:23], v[248:249], v[246:247]
	v_pk_add_f32 v[246:247], v[30:31], v[246:247]
	v_lshlrev_b32_e32 v248, 16, v245
	v_and_b32_e32 v249, 0xffff0000, v245
	v_pk_mul_f32 v[246:247], v[246:247], v[248:249]
	v_cvt_pk_bf16_f32 v201, v246, v247
	global_store_dwordx4 v[152:153], v[198:201], off
	ds_read_b128 v[242:245], v170 offset:61504
	ds_read_b128 v[246:249], v171 offset:44096
	ds_read_b128 v[250:253], v172 offset:44096
	s_waitcnt lgkmcnt(9)
	v_mfma_f32_16x16x32_bf16 v[190:193], v[218:221], v[222:225], 0
	v_mfma_f32_16x16x32_bf16 v[194:197], v[218:221], v[226:229], 0
	ds_read_b64_tr_b16 v[218:219], v178 offset:17408
	ds_read_b64_tr_b16 v[220:221], v178 offset:18496
	ds_read_b64_tr_b16 v[222:223], v161 offset:34880
	ds_read_b64_tr_b16 v[224:225], v161 offset:35456
	ds_read_b64_tr_b16 v[226:227], v161 offset:34912
	ds_read_b64_tr_b16 v[228:229], v161 offset:35488
	s_waitcnt lgkmcnt(9)
	v_mfma_f32_16x16x32_bf16 v[96:99], v[230:233], v[234:237], v[96:99]
	v_mfma_f32_16x16x32_bf16 v[100:103], v[230:233], v[238:241], v[100:103]
	ds_read_b128 v[230:233], v170 offset:61568
	ds_read_b128 v[234:237], v171 offset:44160
	ds_read_b128 v[238:241], v172 offset:44160
	s_waitcnt lgkmcnt(9)
	v_mfma_f32_16x16x32_bf16 v[190:193], v[242:245], v[246:249], v[190:193]
	v_mfma_f32_16x16x32_bf16 v[194:197], v[242:245], v[250:253], v[194:197]
	ds_read_b64_tr_b16 v[242:243], v206 offset:34816
	ds_read_b64_tr_b16 v[244:245], v206 offset:35392
	ds_read_b128 v[246:249], v208
	ds_read_b128 v[250:253], v209
	s_waitcnt lgkmcnt(7)
	v_mfma_f32_16x16x32_bf16 v[104:107], v[218:221], v[222:225], v[104:107]
	v_mfma_f32_16x16x32_bf16 v[214:217], v[218:221], v[226:229], v[108:111]
	ds_read_b128 v[218:221], v170 offset:61632
	ds_read_b128 v[222:225], v171 offset:44224
	ds_read_b128 v[226:229], v172 offset:44224
	s_waitcnt lgkmcnt(7)
	v_mfma_f32_16x16x32_bf16 v[190:193], v[230:233], v[234:237], v[190:193]
	v_mfma_f32_16x16x32_bf16 v[194:197], v[230:233], v[238:241], v[194:197]
	ds_read_b64_tr_b16 v[230:231], v206 offset:39424
	ds_read_b64_tr_b16 v[232:233], v206 offset:40000
	ds_read_b128 v[234:237], v208 offset:64
	ds_read_b128 v[238:241], v209 offset:64
	s_waitcnt lgkmcnt(7)
	v_mfma_f32_16x16x32_bf16 v[198:201], v[242:245], v[246:249], 0
	v_mfma_f32_16x16x32_bf16 v[202:205], v[242:245], v[250:253], 0
	ds_read_b128 v[242:245], v183
	ds_read_b128 v[246:249], v171
	ds_read_b128 v[250:253], v172
	s_waitcnt lgkmcnt(7)
	v_mfma_f32_16x16x32_bf16 v[190:193], v[218:221], v[222:225], v[190:193]
	v_mfma_f32_16x16x32_bf16 v[194:197], v[218:221], v[226:229], v[194:197]
	ds_read_b128 v[218:221], v183 offset:64
	ds_read_b128 v[222:225], v171 offset:64
	ds_read_b128 v[226:229], v172 offset:64
	s_waitcnt lgkmcnt(6)
	v_mfma_f32_16x16x32_bf16 v[198:201], v[230:233], v[234:237], v[198:201]
	v_mfma_f32_16x16x32_bf16 v[202:205], v[230:233], v[238:241], v[202:205]
	ds_read_b128 v[230:233], v183 offset:128
	ds_read_b128 v[234:237], v171 offset:128
	ds_read_b128 v[238:241], v172 offset:128
	v_cndmask_b32_e32 v190, 0, v190, vcc
	v_cndmask_b32_e64 v191, 0, v191, s[6:7]
	v_cndmask_b32_e64 v192, 0, v192, s[8:9]
	v_cndmask_b32_e64 v193, 0, v193, s[10:11]
	v_cvt_pk_bf16_f32 v190, v190, v191
	v_cvt_pk_bf16_f32 v191, v192, v193
	v_cndmask_b32_e64 v194, 0, v194, s[12:13]
	v_cndmask_b32_e64 v195, 0, v195, s[14:15]
	v_cndmask_b32_e64 v196, 0, v196, s[16:17]
	v_cndmask_b32_e64 v197, 0, v197, s[18:19]
	v_cvt_pk_bf16_f32 v194, v194, v195
	v_cvt_pk_bf16_f32 v195, v196, v197
	ds_write_b64 v212, v[190:191]
	ds_write_b64 v213, v[194:195]
	s_waitcnt lgkmcnt(8)
	v_mfma_f32_16x16x32_bf16 v[198:201], v[242:245], v[246:249], v[198:201]
	v_mfma_f32_16x16x32_bf16 v[202:205], v[242:245], v[250:253], v[202:205]
	ds_read_b128 v[242:245], v183 offset:192
	ds_read_b128 v[246:249], v171 offset:192
	ds_read_b128 v[250:253], v172 offset:192
	s_waitcnt lgkmcnt(8)
	v_mfma_f32_16x16x32_bf16 v[198:201], v[218:221], v[222:225], v[198:201]
	v_mfma_f32_16x16x32_bf16 v[202:205], v[218:221], v[226:229], v[202:205]
	ds_read_b64_tr_b16 v[218:219], v178 offset:26112
	ds_read_b64_tr_b16 v[220:221], v178 offset:27200
	ds_read_b64_tr_b16 v[222:223], v161 offset:39424
	ds_read_b64_tr_b16 v[224:225], v161 offset:40000
	ds_read_b64_tr_b16 v[226:227], v161 offset:39456
	ds_read_b64_tr_b16 v[228:229], v161 offset:40032
	s_waitcnt lgkmcnt(11)
	v_mfma_f32_16x16x32_bf16 v[198:201], v[230:233], v[234:237], v[198:201]
	v_mfma_f32_16x16x32_bf16 v[202:205], v[230:233], v[238:241], v[202:205]
	ds_read_b64_tr_b16 v[230:231], v178 offset:26112
	ds_read_b64_tr_b16 v[232:233], v178 offset:27200
	ds_read_b64_tr_b16 v[234:235], v161 offset:39488
	ds_read_b64_tr_b16 v[236:237], v161 offset:40064
	ds_read_b64_tr_b16 v[238:239], v161 offset:39520
	ds_read_b64_tr_b16 v[240:241], v161 offset:40096
	s_waitcnt lgkmcnt(12)
	v_mfma_f32_16x16x32_bf16 v[198:201], v[242:245], v[246:249], v[198:201]
	v_mfma_f32_16x16x32_bf16 v[202:205], v[242:245], v[250:253], v[202:205]
	s_waitcnt lgkmcnt(6)
	v_mfma_f32_16x16x32_bf16 v[112:115], v[218:221], v[222:225], v[96:99]
	v_mfma_f32_16x16x32_bf16 v[108:111], v[218:221], v[226:229], v[100:103]
	s_nop 3
	v_cvt_pk_bf16_f32 v198, v198, v199
	v_cvt_pk_bf16_f32 v199, v200, v201
	v_add_u32_e32 v254, s48, v173
	v_mad_u64_u32 v[254:255], s[20:21], v254, s42, 0
	v_lshl_add_u64 v[254:255], v[254:255], 1, v[150:151]
	v_cvt_pk_bf16_f32 v202, v202, v203
	v_cvt_pk_bf16_f32 v203, v204, v205
	global_store_dwordx2 v[254:255], v[198:199], off
	v_add_u32_e32 v254, s48, v179
	v_mad_u64_u32 v[254:255], s[20:21], v254, s42, 0
	v_lshl_add_u64 v[254:255], v[254:255], 1, v[150:151]
	global_store_dwordx2 v[254:255], v[202:203], off
	s_waitcnt lgkmcnt(0)
	v_mfma_f32_16x16x32_bf16 v[104:107], v[230:233], v[234:237], v[104:107]
	v_mfma_f32_16x16x32_bf16 v[100:103], v[230:233], v[238:241], v[214:217]
	s_min_u32 s20, s44, 59
	s_waitcnt lgkmcnt(0)
	s_barrier
	s_waitcnt vmcnt(20)
	ds_write_b128 v168, v[72:75]
	s_waitcnt vmcnt(19)
	ds_write_b128 v168, v[80:83] offset:8704
	s_waitcnt vmcnt(18)
	ds_write_b128 v168, v[76:79] offset:17408
	s_waitcnt vmcnt(17)
	ds_write_b128 v168, v[84:87] offset:26112
	s_waitcnt vmcnt(16)
	ds_write_b128 v169, v[88:91] offset:34816
	v_add_u32_e32 v72, s34, v154
	s_add_i32 s34, s20, 4
	s_waitcnt vmcnt(15)
	s_cmp_lg_u32 s69, 0
	s_cbranch_scc1 .Lev_skip_b
	ds_write_b128 v72, v[92:95]
